# merge-GEMM hook: second half's 16 gate loads issued together with the first half's (dead fragment registers), one wait per half
# speedup vs baseline: 1.0074x; 1.0045x over previous
; #define PG8_STAGE(bufoff, gbase, voff) do { _Pragma("unroll") for (int _i = 0; _i < 2; ++_i) \
;         __builtin_amdgcn_global_load_lds((const unsigned*)((const char*)(gbase) + (voff)[_i]), (LAS unsigned*)(lds + (bufoff) + ldsw + _i * 8192), 16, 0, 0); } while (0)
; #define PG8_LDA(dst, b, h) do { _Pragma("unroll") for (int m = 0; m < 4; ++m) _Pragma("unroll") for (int k = 0; k < 2; ++k) dst[m][k] = *(const LAS bf16x8*)(lds + PG8_SA(b, h) + aoff + m * 2048 + k * 1024); } while (0)
; #define PG8_LDB(dst, b, h) do { _Pragma("unroll") for (int n = 0; n < 2; ++n) _Pragma("unroll") for (int k = 0; k < 2; ++k) dst[n][k] = *(const LAS bf16x8*)(lds + PG8_SB(b, h) + boff + n * 2048 + k * 1024); } while (0)
; #define PG8_MMA(ai, bj, At, Bt) do { __builtin_amdgcn_s_setprio(1); _Pragma("unroll") for (int m = 0; m < 4; ++m) _Pragma("unroll") for (int n = 0; n < 2; ++n) _Pragma("unroll") for (int k = 0; k < 2; ++k) \
;         acc[ai][bj][m][n] = __builtin_amdgcn_mfma_f32_16x16x32_bf16(Bt[n][k], At[m][k], acc[ai][bj][m][n], 0, 0, 0); __builtin_amdgcn_s_setprio(0); } while (0)
; #define PG8_WAIT_L(n) asm volatile("s_waitcnt lgkmcnt(" #n ")" ::: "memory")
; #define PG8_BAR __builtin_amdgcn_s_barrier()
; #define PG8_SCHED __builtin_amdgcn_sched_barrier(0)
; template <class Epi, class Sched>
; __device__ __forceinline__ void gemm_phase(LAS unsigned char* lds, const Gemm g, const Sched& S, const Epi& E) {
;     ...
;             PG8_LDB(B0, 0, 0); PG8_SCHED; PG8_LDA(At, 0, 0); PG8_STAGE(PG8_SA(1, 1), a1 + hstepA, voffA);
;             PG8_WAIT_L(8); PG8_BAR; PG8_WAIT_L(0); PG8_MMA(0, 0, At, B0); PG8_BAR; PG8_SCHED;
;             PG8_LDB(B1, 0, 1); PG8_STAGE(PG8_SB(0, 0), b2, voffB);
;             PG8_BAR; PG8_WAIT_L(0); PG8_MMA(0, 1, At, B1); PG8_BAR;
;             PG8_LDA(At, 0, 1); PG8_STAGE(PG8_SA(0, 0), a2, voffA);
;             PG8_BAR; PG8_WAIT_L(0); PG8_MMA(1, 0, At, B0); PG8_BAR; PG8_SCHED;
.LBB0_45:
	s_add_i32 s58, s58, 2
	s_add_u32 s22, s18, 0xfffc0080
	s_addc_u32 s23, s19, -1
	s_add_i32 s60, 0, 0x10000
	v_add_u32_e32 v1, s60, v178
	ds_read_b128 v[144:147], v1
	ds_read_b128 v[148:151], v1 offset:1024
	ds_read_b128 v[152:155], v1 offset:2048
	ds_read_b128 v[156:159], v1 offset:3072
	s_cmpk_eq_i32 s59, 0xe00
	s_cselect_b64 s[2:3], -1, 0
	s_and_b64 s[20:21], s[2:3], exec
	s_cselect_b32 s23, s0, s23
	s_cselect_b32 s22, s1, s22
	s_cselect_b32 s21, s46, s49
	s_cselect_b32 s20, s47, s48
	v_lshl_add_u64 v[2:3], s[18:19], 0, v[142:143]
	s_add_i32 m0, s38, 0xc000
	ds_read_b128 v[160:163], v179
	ds_read_b128 v[164:167], v179 offset:1024
	ds_read_b128 v[168:171], v179 offset:2048
	ds_read_b128 v[172:175], v179 offset:3072
	ds_read_b128 v[180:183], v179 offset:4096
	ds_read_b128 v[184:187], v179 offset:5120
	ds_read_b128 v[190:193], v179 offset:6144
	ds_read_b128 v[194:197], v179 offset:7168
	global_load_lds_dwordx4 v[2:3], off
	v_lshl_add_u64 v[2:3], s[18:19], 0, v[140:141]
	s_add_i32 m0, s38, 0xe000
	s_nop 0
	global_load_lds_dwordx4 v[2:3], off
	s_waitcnt lgkmcnt(8)
	s_barrier
	s_waitcnt lgkmcnt(0)
	s_setprio 1
	s_waitcnt lgkmcnt(0)
	v_mfma_f32_16x16x32_bf16 v[128:131], v[144:147], v[160:163], v[128:131]
	v_mfma_f32_16x16x32_bf16 v[124:127], v[152:155], v[160:163], v[124:127]
	v_mfma_f32_16x16x32_bf16 v[112:115], v[144:147], v[168:171], v[112:115]
	v_mfma_f32_16x16x32_bf16 v[108:111], v[152:155], v[168:171], v[108:111]
	v_mfma_f32_16x16x32_bf16 v[96:99], v[144:147], v[180:183], v[96:99]
	v_mfma_f32_16x16x32_bf16 v[92:95], v[152:155], v[180:183], v[92:95]
	v_mfma_f32_16x16x32_bf16 v[80:83], v[144:147], v[190:193], v[80:83]
	v_mfma_f32_16x16x32_bf16 v[76:79], v[152:155], v[190:193], v[76:79]
	v_mfma_f32_16x16x32_bf16 v[128:131], v[148:151], v[164:167], v[128:131]
	v_mfma_f32_16x16x32_bf16 v[124:127], v[156:159], v[164:167], v[124:127]
	v_mfma_f32_16x16x32_bf16 v[112:115], v[148:151], v[172:175], v[112:115]
	v_mfma_f32_16x16x32_bf16 v[108:111], v[156:159], v[172:175], v[108:111]
	v_mfma_f32_16x16x32_bf16 v[96:99], v[148:151], v[184:187], v[96:99]
	v_mfma_f32_16x16x32_bf16 v[92:95], v[156:159], v[184:187], v[92:95]
	v_mfma_f32_16x16x32_bf16 v[80:83], v[148:151], v[194:197], v[80:83]
	v_mfma_f32_16x16x32_bf16 v[76:79], v[156:159], v[194:197], v[76:79]
	s_setprio 0
	s_barrier
	s_add_i32 s62, 0, 0x14000
	s_add_i32 s60, s60, s34
	v_add_u32_e32 v1, s62, v178
	v_lshl_add_u64 v[176:177], s[20:21], 0, v[136:137]
	s_mov_b32 m0, s60
	ds_read_b128 v[200:203], v1
	ds_read_b128 v[204:207], v1 offset:1024
	ds_read_b128 v[208:211], v1 offset:2048
	ds_read_b128 v[212:215], v1 offset:3072
	global_load_lds_dwordx4 v[176:177], off
	v_lshl_add_u64 v[198:199], s[20:21], 0, v[132:133]
	s_add_i32 m0, s60, 0x2000
	s_nop 0
	global_load_lds_dwordx4 v[198:199], off
	s_barrier
	s_waitcnt lgkmcnt(0)
	s_setprio 1
	s_waitcnt lgkmcnt(0)
	v_mfma_f32_16x16x32_bf16 v[120:123], v[200:203], v[160:163], v[120:123]
	v_mfma_f32_16x16x32_bf16 v[116:119], v[208:211], v[160:163], v[116:119]
	v_mfma_f32_16x16x32_bf16 v[104:107], v[200:203], v[168:171], v[104:107]
	v_mfma_f32_16x16x32_bf16 v[100:103], v[208:211], v[168:171], v[100:103]
	v_mfma_f32_16x16x32_bf16 v[88:91], v[200:203], v[180:183], v[88:91]
	v_mfma_f32_16x16x32_bf16 v[84:87], v[208:211], v[180:183], v[84:87]
	v_mfma_f32_16x16x32_bf16 v[72:75], v[200:203], v[190:193], v[72:75]
	v_mfma_f32_16x16x32_bf16 v[68:71], v[208:211], v[190:193], v[68:71]
	v_mfma_f32_16x16x32_bf16 v[120:123], v[204:207], v[164:167], v[120:123]
	v_mfma_f32_16x16x32_bf16 v[116:119], v[212:215], v[164:167], v[116:119]
	v_mfma_f32_16x16x32_bf16 v[104:107], v[204:207], v[172:175], v[104:107]
	v_mfma_f32_16x16x32_bf16 v[100:103], v[212:215], v[172:175], v[100:103]
	v_mfma_f32_16x16x32_bf16 v[88:91], v[204:207], v[184:187], v[88:91]
	v_mfma_f32_16x16x32_bf16 v[84:87], v[212:215], v[184:187], v[84:87]
	v_mfma_f32_16x16x32_bf16 v[72:75], v[204:207], v[194:197], v[72:75]
	v_mfma_f32_16x16x32_bf16 v[68:71], v[212:215], v[194:197], v[68:71]
	s_setprio 0
	s_mov_b32 m0, s38
	v_lshl_add_u64 v[216:217], s[22:23], 0, v[138:139]
	s_barrier
	ds_read_b128 v[160:163], v179 offset:16384
	ds_read_b128 v[164:167], v179 offset:17408
	ds_read_b128 v[168:171], v179 offset:18432
	ds_read_b128 v[172:175], v179 offset:19456
	ds_read_b128 v[180:183], v179 offset:20480
	ds_read_b128 v[184:187], v179 offset:21504
	ds_read_b128 v[190:193], v179 offset:22528
	ds_read_b128 v[194:197], v179 offset:23552
	global_load_lds_dwordx4 v[216:217], off
	v_lshl_add_u64 v[218:219], s[22:23], 0, v[134:135]
	s_mov_b32 m0, s39
	s_nop 0
	global_load_lds_dwordx4 v[218:219], off
	s_barrier
	s_waitcnt lgkmcnt(0)
	s_setprio 1
	s_waitcnt lgkmcnt(0)
	v_mfma_f32_16x16x32_bf16 v[64:67], v[144:147], v[160:163], v[64:67]
	v_mfma_f32_16x16x32_bf16 v[60:63], v[152:155], v[160:163], v[60:63]
	v_mfma_f32_16x16x32_bf16 v[48:51], v[144:147], v[168:171], v[48:51]
	v_mfma_f32_16x16x32_bf16 v[44:47], v[152:155], v[168:171], v[44:47]
	v_mfma_f32_16x16x32_bf16 v[32:35], v[144:147], v[180:183], v[32:35]
	v_mfma_f32_16x16x32_bf16 v[28:31], v[152:155], v[180:183], v[28:31]
	v_mfma_f32_16x16x32_bf16 v[16:19], v[144:147], v[190:193], v[16:19]
	v_mfma_f32_16x16x32_bf16 v[12:15], v[152:155], v[190:193], v[12:15]
	v_mfma_f32_16x16x32_bf16 v[64:67], v[148:151], v[164:167], v[64:67]
	v_mfma_f32_16x16x32_bf16 v[60:63], v[156:159], v[164:167], v[60:63]
	v_mfma_f32_16x16x32_bf16 v[48:51], v[148:151], v[172:175], v[48:51]
	v_mfma_f32_16x16x32_bf16 v[44:47], v[156:159], v[172:175], v[44:47]
	v_mfma_f32_16x16x32_bf16 v[32:35], v[148:151], v[184:187], v[32:35]
	v_mfma_f32_16x16x32_bf16 v[28:31], v[156:159], v[184:187], v[28:31]
	v_mfma_f32_16x16x32_bf16 v[16:19], v[148:151], v[194:197], v[16:19]
	v_mfma_f32_16x16x32_bf16 v[12:15], v[156:159], v[194:197], v[12:15]
	s_setprio 0
	s_barrier
; #define PG8_STAGE(bufoff, gbase, voff) do { _Pragma("unroll") for (int _i = 0; _i < 2; ++_i) \
;         __builtin_amdgcn_global_load_lds((const unsigned*)((const char*)(gbase) + (voff)[_i]), (LAS unsigned*)(lds + (bufoff) + ldsw + _i * 8192), 16, 0, 0); } while (0)
; #define PG8_LDA(dst, b, h) do { _Pragma("unroll") for (int m = 0; m < 4; ++m) _Pragma("unroll") for (int k = 0; k < 2; ++k) dst[m][k] = *(const LAS bf16x8*)(lds + PG8_SA(b, h) + aoff + m * 2048 + k * 1024); } while (0)
; #define PG8_LDB(dst, b, h) do { _Pragma("unroll") for (int n = 0; n < 2; ++n) _Pragma("unroll") for (int k = 0; k < 2; ++k) dst[n][k] = *(const LAS bf16x8*)(lds + PG8_SB(b, h) + boff + n * 2048 + k * 1024); } while (0)
; #define PG8_MMA(ai, bj, At, Bt) do { __builtin_amdgcn_s_setprio(1); _Pragma("unroll") for (int m = 0; m < 4; ++m) _Pragma("unroll") for (int n = 0; n < 2; ++n) _Pragma("unroll") for (int k = 0; k < 2; ++k) \
;         acc[ai][bj][m][n] = __builtin_amdgcn_mfma_f32_16x16x32_bf16(Bt[n][k], At[m][k], acc[ai][bj][m][n], 0, 0, 0); __builtin_amdgcn_s_setprio(0); } while (0)
; #define PG8_WAIT_V(n) asm volatile("s_waitcnt vmcnt(" #n ")" ::: "memory")
; #define PG8_WAIT_L(n) asm volatile("s_waitcnt lgkmcnt(" #n ")" ::: "memory")
; #define PG8_BAR __builtin_amdgcn_s_barrier()
; #define PG8_SCHED __builtin_amdgcn_sched_barrier(0)
; template <class Epi, class Sched>
; __device__ __forceinline__ void gemm_phase(LAS unsigned char* lds, const Gemm g, const Sched& S, const Epi& E) {
;     ...
;             PG8_STAGE(PG8_SB(0, 1), b2 + hstepB, voffB);
;             PG8_WAIT_V(6); PG8_BAR; PG8_MMA(1, 1, At, B1); PG8_BAR;
;             PG8_LDB(B0, 1, 0); PG8_SCHED; PG8_LDA(At, 1, 0); PG8_STAGE(PG8_SA(0, 1), a2 + hstepA, voffA);
;             PG8_WAIT_L(8); PG8_BAR; PG8_WAIT_L(0); PG8_MMA(0, 0, At, B0); PG8_BAR; PG8_SCHED;
;             PG8_LDB(B1, 1, 1); PG8_STAGE(PG8_SB(1, 0), b3, voffB);
;             PG8_BAR; PG8_WAIT_L(0); PG8_MMA(0, 1, At, B1); PG8_BAR;
;             PG8_LDA(At, 1, 1); PG8_STAGE(PG8_SA(1, 0), a3, voffA);
;             PG8_BAR; PG8_WAIT_L(0); PG8_MMA(1, 0, At, B0); PG8_BAR; PG8_SCHED;
	s_add_u32 s60, s20, 0x40000
	s_addc_u32 s61, s21, 0
	s_add_i32 s62, s62, s34
	v_lshl_add_u64 v[2:3], s[60:61], 0, v[136:137]
	s_mov_b32 m0, s62
	s_nop 0
	global_load_lds_dwordx4 v[2:3], off
	v_lshl_add_u64 v[2:3], s[60:61], 0, v[132:133]
	s_add_i32 m0, s62, 0x2000
	s_nop 0
	global_load_lds_dwordx4 v[2:3], off
	s_waitcnt vmcnt(6)
	s_barrier
	s_setprio 1
	v_mfma_f32_16x16x32_bf16 v[56:59], v[200:203], v[160:163], v[56:59]
	v_mfma_f32_16x16x32_bf16 v[52:55], v[208:211], v[160:163], v[52:55]
	v_mfma_f32_16x16x32_bf16 v[40:43], v[200:203], v[168:171], v[40:43]
	v_mfma_f32_16x16x32_bf16 v[36:39], v[208:211], v[168:171], v[36:39]
	v_mfma_f32_16x16x32_bf16 v[24:27], v[200:203], v[180:183], v[24:27]
	v_mfma_f32_16x16x32_bf16 v[20:23], v[208:211], v[180:183], v[20:23]
	v_mfma_f32_16x16x32_bf16 v[8:11], v[200:203], v[190:193], v[8:11]
	v_mfma_f32_16x16x32_bf16 v[2:5], v[208:211], v[190:193], v[4:7]
	v_mfma_f32_16x16x32_bf16 v[56:59], v[204:207], v[164:167], v[56:59]
	v_mfma_f32_16x16x32_bf16 v[52:55], v[212:215], v[164:167], v[52:55]
	v_mfma_f32_16x16x32_bf16 v[40:43], v[204:207], v[172:175], v[40:43]
	v_mfma_f32_16x16x32_bf16 v[36:39], v[212:215], v[172:175], v[36:39]
	v_mfma_f32_16x16x32_bf16 v[24:27], v[204:207], v[184:187], v[24:27]
	v_mfma_f32_16x16x32_bf16 v[20:23], v[212:215], v[184:187], v[20:23]
	v_mfma_f32_16x16x32_bf16 v[8:11], v[204:207], v[194:197], v[8:11]
	v_mfma_f32_16x16x32_bf16 v[2:5], v[212:215], v[194:197], v[2:5]
	s_setprio 0
	s_add_i32 s60, 0, 0x18000
	v_add_u32_e32 v1, s60, v178
	s_barrier
	ds_read_b128 v[144:147], v1
	ds_read_b128 v[148:151], v1 offset:1024
	ds_read_b128 v[152:155], v1 offset:2048
	ds_read_b128 v[156:159], v1 offset:3072
	s_add_u32 s22, s22, 0x40000
	s_addc_u32 s23, s23, 0
	s_mov_b32 m0, s40
	v_lshl_add_u64 v[6:7], s[22:23], 0, v[138:139]
	ds_read_b128 v[160:163], v179 offset:32768
	ds_read_b128 v[164:167], v179 offset:33792
	ds_read_b128 v[168:171], v179 offset:34816
	ds_read_b128 v[172:175], v179 offset:35840
	ds_read_b128 v[180:183], v179 offset:36864
	ds_read_b128 v[184:187], v179 offset:37888
	ds_read_b128 v[190:193], v179 offset:38912
	ds_read_b128 v[194:197], v179 offset:39936
	global_load_lds_dwordx4 v[6:7], off
	v_lshl_add_u64 v[6:7], s[22:23], 0, v[134:135]
	s_mov_b32 m0, s41
	s_nop 0
	global_load_lds_dwordx4 v[6:7], off
	s_waitcnt lgkmcnt(8)
	s_barrier
	s_waitcnt lgkmcnt(0)
	s_setprio 1
	s_waitcnt lgkmcnt(0)
	v_mfma_f32_16x16x32_bf16 v[128:131], v[144:147], v[160:163], v[128:131]
	v_mfma_f32_16x16x32_bf16 v[124:127], v[152:155], v[160:163], v[124:127]
	v_mfma_f32_16x16x32_bf16 v[112:115], v[144:147], v[168:171], v[112:115]
	v_mfma_f32_16x16x32_bf16 v[108:111], v[152:155], v[168:171], v[108:111]
	v_mfma_f32_16x16x32_bf16 v[96:99], v[144:147], v[180:183], v[96:99]
	v_mfma_f32_16x16x32_bf16 v[92:95], v[152:155], v[180:183], v[92:95]
	v_mfma_f32_16x16x32_bf16 v[80:83], v[144:147], v[190:193], v[80:83]
	v_mfma_f32_16x16x32_bf16 v[76:79], v[152:155], v[190:193], v[76:79]
	v_mfma_f32_16x16x32_bf16 v[128:131], v[148:151], v[164:167], v[128:131]
	v_mfma_f32_16x16x32_bf16 v[124:127], v[156:159], v[164:167], v[124:127]
	v_mfma_f32_16x16x32_bf16 v[112:115], v[148:151], v[172:175], v[112:115]
	v_mfma_f32_16x16x32_bf16 v[108:111], v[156:159], v[172:175], v[108:111]
	v_mfma_f32_16x16x32_bf16 v[96:99], v[148:151], v[184:187], v[96:99]
	v_mfma_f32_16x16x32_bf16 v[92:95], v[156:159], v[184:187], v[92:95]
	v_mfma_f32_16x16x32_bf16 v[80:83], v[148:151], v[194:197], v[80:83]
	v_mfma_f32_16x16x32_bf16 v[76:79], v[156:159], v[194:197], v[76:79]
	s_setprio 0
	s_barrier
	s_add_i32 s22, 0, 0x1c000
	s_add_i32 s23, s60, s34
	v_add_u32_e32 v1, s22, v178
	v_lshl_add_u64 v[6:7], v[176:177], 0, s[90:91]
	s_mov_b32 m0, s23
	ds_read_b128 v[200:203], v1
	ds_read_b128 v[204:207], v1 offset:1024
	ds_read_b128 v[208:211], v1 offset:2048
	ds_read_b128 v[212:215], v1 offset:3072
	global_load_lds_dwordx4 v[6:7], off
	v_lshl_add_u64 v[6:7], v[198:199], 0, s[90:91]
	s_add_i32 m0, s23, 0x2000
	s_nop 0
	global_load_lds_dwordx4 v[6:7], off
	s_barrier
	s_waitcnt lgkmcnt(0)
	s_setprio 1
	s_waitcnt lgkmcnt(0)
	v_mfma_f32_16x16x32_bf16 v[120:123], v[200:203], v[160:163], v[120:123]
	v_mfma_f32_16x16x32_bf16 v[116:119], v[208:211], v[160:163], v[116:119]
	v_mfma_f32_16x16x32_bf16 v[104:107], v[200:203], v[168:171], v[104:107]
	v_mfma_f32_16x16x32_bf16 v[100:103], v[208:211], v[168:171], v[100:103]
	v_mfma_f32_16x16x32_bf16 v[88:91], v[200:203], v[180:183], v[88:91]
	v_mfma_f32_16x16x32_bf16 v[84:87], v[208:211], v[180:183], v[84:87]
	v_mfma_f32_16x16x32_bf16 v[72:75], v[200:203], v[190:193], v[72:75]
	v_mfma_f32_16x16x32_bf16 v[68:71], v[208:211], v[190:193], v[68:71]
	v_mfma_f32_16x16x32_bf16 v[120:123], v[204:207], v[164:167], v[120:123]
	v_mfma_f32_16x16x32_bf16 v[116:119], v[212:215], v[164:167], v[116:119]
	v_mfma_f32_16x16x32_bf16 v[104:107], v[204:207], v[172:175], v[104:107]
	v_mfma_f32_16x16x32_bf16 v[100:103], v[212:215], v[172:175], v[100:103]
	v_mfma_f32_16x16x32_bf16 v[88:91], v[204:207], v[184:187], v[88:91]
	v_mfma_f32_16x16x32_bf16 v[84:87], v[212:215], v[184:187], v[84:87]
	v_mfma_f32_16x16x32_bf16 v[72:75], v[204:207], v[194:197], v[72:75]
	v_mfma_f32_16x16x32_bf16 v[68:71], v[212:215], v[194:197], v[68:71]
	s_setprio 0
	s_mov_b32 m0, s42
	v_lshl_add_u64 v[6:7], v[216:217], 0, s[90:91]
	s_barrier
	ds_read_b128 v[160:163], v179 offset:49152
	ds_read_b128 v[164:167], v179 offset:50176
	ds_read_b128 v[168:171], v179 offset:51200
	ds_read_b128 v[172:175], v179 offset:52224
	ds_read_b128 v[180:183], v179 offset:53248
	ds_read_b128 v[184:187], v179 offset:54272
	ds_read_b128 v[190:193], v179 offset:55296
	ds_read_b128 v[194:197], v179 offset:56320
	global_load_lds_dwordx4 v[6:7], off
	v_lshl_add_u64 v[6:7], v[218:219], 0, s[90:91]
	s_mov_b32 m0, s43
	s_nop 0
	global_load_lds_dwordx4 v[6:7], off
	s_barrier
; __device__ __forceinline__ int opaque_tid() { int t = threadIdx.x; asm volatile("" : "+v"(t)); return t; }
; #define PG8_STAGE(bufoff, gbase, voff) do { _Pragma("unroll") for (int _i = 0; _i < 2; ++_i) \
;         __builtin_amdgcn_global_load_lds((const unsigned*)((const char*)(gbase) + (voff)[_i]), (LAS unsigned*)(lds + (bufoff) + ldsw + _i * 8192), 16, 0, 0); } while (0)
; #define PG8_MMA(ai, bj, At, Bt) do { __builtin_amdgcn_s_setprio(1); _Pragma("unroll") for (int m = 0; m < 4; ++m) _Pragma("unroll") for (int n = 0; n < 2; ++n) _Pragma("unroll") for (int k = 0; k < 2; ++k) \
;         acc[ai][bj][m][n] = __builtin_amdgcn_mfma_f32_16x16x32_bf16(Bt[n][k], At[m][k], acc[ai][bj][m][n], 0, 0, 0); __builtin_amdgcn_s_setprio(0); } while (0)
; #define PG8_WAIT_V(n) asm volatile("s_waitcnt vmcnt(" #n ")" ::: "memory")
; #define PG8_WAIT_L(n) asm volatile("s_waitcnt lgkmcnt(" #n ")" ::: "memory")
; #define PG8_BAR __builtin_amdgcn_s_barrier()
; #define PG8_SCHED __builtin_amdgcn_sched_barrier(0)
; template <class Epi, class Sched>
; __device__ __forceinline__ void gemm_phase(LAS unsigned char* lds, const Gemm g, const Sched& S, const Epi& E) {
;     ...
;             PG8_BAR; PG8_WAIT_L(0); PG8_MMA(1, 0, At, B0); PG8_BAR; PG8_SCHED;
;             PG8_STAGE(PG8_SB(1, 1), b3 + hstepB, voffB);
;             PG8_WAIT_V(6); PG8_BAR; PG8_MMA(1, 1, At, B1); PG8_BAR;
;             if constexpr (Epi::HOOK) { if ((((t + 2) & 3) == 0) && !last) E.hook(acc, cur, (t + 2) >> 2, wr, wc, fr, fq); }
;     __device__ __forceinline__ void hook(f32x4 (&acc)[2][2][4][2], const Unit& u, int nb, int wr, int wc, int fr, int fq) const {
;         { const int t_ = opaque_tid(); wr = t_ >> 8; wc = (t_ >> 6) & 3; fr = t_ & 15; fq = (t_ >> 4) & 3; }
;         const int row0 = u.pm * 256 + wr * 64 + fr, c0 = u.pn * 256 + wc * 32 + 8 * fq;
; #pragma unroll
;         for (int ai = 0; ai < 2; ++ai) {
;             u32x2 ga[4][2], gb[4][2];
; #pragma unroll
;             for (int m = 0; m < 4; ++m)
; #pragma unroll
;                 for (int bj = 0; bj < 2; ++bj) { const int row = row0 + ai * 128 + m * 16, c = c0 + bj * 128;
;                     ga[m][bj] = *(const u32x2*)(G8 + g8_off(row, (nb - 1) * 1024 + c)); gb[m][bj] = *(const u32x2*)(G8 + g8_off(row, nb * 1024 + c)); }
	s_waitcnt lgkmcnt(0)
	s_setprio 1
	s_waitcnt lgkmcnt(0)
	v_mfma_f32_16x16x32_bf16 v[64:67], v[144:147], v[160:163], v[64:67]
	v_mfma_f32_16x16x32_bf16 v[60:63], v[152:155], v[160:163], v[60:63]
	v_mfma_f32_16x16x32_bf16 v[48:51], v[144:147], v[168:171], v[48:51]
	v_mfma_f32_16x16x32_bf16 v[44:47], v[152:155], v[168:171], v[44:47]
	v_mfma_f32_16x16x32_bf16 v[32:35], v[144:147], v[180:183], v[32:35]
	v_mfma_f32_16x16x32_bf16 v[28:31], v[152:155], v[180:183], v[28:31]
	v_mfma_f32_16x16x32_bf16 v[16:19], v[144:147], v[190:193], v[16:19]
	v_mfma_f32_16x16x32_bf16 v[12:15], v[152:155], v[190:193], v[12:15]
	v_mfma_f32_16x16x32_bf16 v[64:67], v[148:151], v[164:167], v[64:67]
	v_mfma_f32_16x16x32_bf16 v[60:63], v[156:159], v[164:167], v[60:63]
	v_mfma_f32_16x16x32_bf16 v[48:51], v[148:151], v[172:175], v[48:51]
	v_mfma_f32_16x16x32_bf16 v[44:47], v[156:159], v[172:175], v[44:47]
	v_mfma_f32_16x16x32_bf16 v[32:35], v[148:151], v[184:187], v[32:35]
	v_mfma_f32_16x16x32_bf16 v[28:31], v[156:159], v[184:187], v[28:31]
	v_mfma_f32_16x16x32_bf16 v[16:19], v[148:151], v[194:197], v[16:19]
	v_mfma_f32_16x16x32_bf16 v[12:15], v[156:159], v[194:197], v[12:15]
	s_setprio 0
	s_barrier
	s_add_u32 s20, s20, 0x40080
	s_addc_u32 s21, s21, 0
	s_add_i32 s22, s22, s34
	v_lshl_add_u64 v[6:7], s[20:21], 0, v[136:137]
	s_mov_b32 m0, s22
	s_nop 0
	global_load_lds_dwordx4 v[6:7], off
	v_lshl_add_u64 v[6:7], s[20:21], 0, v[132:133]
	s_add_i32 m0, s22, 0x2000
	s_nop 0
	global_load_lds_dwordx4 v[6:7], off
	s_waitcnt vmcnt(6)
	s_barrier
	s_setprio 1
	v_mfma_f32_16x16x32_bf16 v[56:59], v[200:203], v[160:163], v[56:59]
	v_mfma_f32_16x16x32_bf16 v[52:55], v[208:211], v[160:163], v[52:55]
	v_mfma_f32_16x16x32_bf16 v[40:43], v[200:203], v[168:171], v[40:43]
	v_mfma_f32_16x16x32_bf16 v[36:39], v[208:211], v[168:171], v[36:39]
	v_mfma_f32_16x16x32_bf16 v[24:27], v[200:203], v[180:183], v[24:27]
	v_mfma_f32_16x16x32_bf16 v[20:23], v[208:211], v[180:183], v[20:23]
	v_mfma_f32_16x16x32_bf16 v[6:9], v[200:203], v[190:193], v[8:11]
	v_mfma_f32_16x16x32_bf16 v[2:5], v[208:211], v[190:193], v[2:5]
	v_mfma_f32_16x16x32_bf16 v[56:59], v[204:207], v[164:167], v[56:59]
	v_mfma_f32_16x16x32_bf16 v[52:55], v[212:215], v[164:167], v[52:55]
	v_mfma_f32_16x16x32_bf16 v[40:43], v[204:207], v[172:175], v[40:43]
	v_mfma_f32_16x16x32_bf16 v[36:39], v[212:215], v[172:175], v[36:39]
	v_mfma_f32_16x16x32_bf16 v[24:27], v[204:207], v[184:187], v[24:27]
	v_mfma_f32_16x16x32_bf16 v[20:23], v[212:215], v[184:187], v[20:23]
	v_mfma_f32_16x16x32_bf16 v[8:11], v[204:207], v[194:197], v[6:9]
	v_mfma_f32_16x16x32_bf16 v[4:7], v[212:215], v[194:197], v[2:5]
	s_setprio 0
	s_bitcmp0_b32 s58, 1
	s_cselect_b64 s[20:21], -1, 0
	s_or_b64 s[2:3], s[2:3], s[20:21]
	s_and_b64 vcc, exec, s[2:3]
	s_barrier
	s_cbranch_vccnz .LBB0_44
	v_mov_b32_e32 v1, v189
	v_mov_b32_e32 v145, v0
	v_and_b32_e32 v2, 15, v1
	v_ashrrev_i32_e32 v3, 2, v1
	v_and_b32_e32 v3, 0xffffffc0, v3
	v_lshrrev_b32_e32 v144, 1, v1
	v_or_b32_e32 v1, s13, v2
	v_add_u32_e32 v1, v1, v3
	v_and_b32_e32 v146, 0x78, v144
	v_and_b32_e32 v144, 24, v144
	v_ashrrev_i32_e32 v152, 4, v1
	v_lshlrev_b32_e32 v2, 5, v2
	v_mov_b32_e32 v3, v0
	v_lshl_add_u64 v[144:145], s[6:7], 0, v[144:145]
	s_add_i32 s2, s11, s59
	v_ashrrev_i32_e32 v153, 31, v152
	v_lshl_add_u64 v[148:149], v[144:145], 0, v[2:3]
	v_add_u32_e32 v146, s2, v146
	v_lshlrev_b64 v[2:3], 16, v[152:153]
	v_lshl_add_u64 v[154:155], v[148:149], 0, v[2:3]
	v_add_u32_e32 v2, 0x200, v146
	v_ashrrev_i32_e32 v2, 5, v2
	v_ashrrev_i32_e32 v3, 31, v2
	v_lshlrev_b64 v[2:3], 9, v[2:3]
	v_lshl_add_u64 v[144:145], v[154:155], 0, v[2:3]
	v_add_u32_e32 v147, 0xfffffe80, v146
	global_load_dwordx2 v[172:173], v[144:145], off
	v_add_u32_e32 v144, 0xfffffe00, v146
	v_add_u32_e32 v150, 0x280, v146
	v_ashrrev_i32_e32 v146, 5, v147
	v_ashrrev_i32_e32 v144, 5, v144
	v_ashrrev_i32_e32 v158, 5, v150
	v_ashrrev_i32_e32 v147, 31, v146
	v_ashrrev_i32_e32 v145, 31, v144
	v_ashrrev_i32_e32 v159, 31, v158
	v_lshlrev_b64 v[150:151], 9, v[146:147]
	v_lshlrev_b64 v[144:145], 9, v[144:145]
	v_lshlrev_b64 v[146:147], 9, v[158:159]
	v_lshl_add_u64 v[158:159], v[154:155], 0, v[150:151]
	v_lshl_add_u64 v[156:157], v[154:155], 0, v[144:145]
	v_lshl_add_u64 v[154:155], v[154:155], 0, v[146:147]
	global_load_dwordx2 v[174:175], v[158:159], off
	global_load_dwordx2 v[176:177], v[154:155], off
	global_load_dwordx2 v[180:181], v[156:157], off
	v_or_b32_e32 v154, 1, v152
	v_or_b32_e32 v156, 2, v152
	v_or_b32_e32 v152, 3, v152
	v_ashrrev_i32_e32 v155, 31, v154
	v_ashrrev_i32_e32 v157, 31, v156
	v_ashrrev_i32_e32 v153, 31, v152
	v_lshlrev_b64 v[154:155], 16, v[154:155]
	v_lshlrev_b64 v[156:157], 16, v[156:157]
	v_lshlrev_b64 v[152:153], 16, v[152:153]
	v_lshl_add_u64 v[154:155], v[148:149], 0, v[154:155]
	v_lshl_add_u64 v[156:157], v[148:149], 0, v[156:157]
	v_lshl_add_u64 v[152:153], v[148:149], 0, v[152:153]
	v_lshl_add_u64 v[158:159], v[154:155], 0, v[144:145]
	v_lshl_add_u64 v[160:161], v[154:155], 0, v[2:3]
	v_lshl_add_u64 v[162:163], v[154:155], 0, v[150:151]
	v_lshl_add_u64 v[154:155], v[154:155], 0, v[146:147]
	v_lshl_add_u64 v[164:165], v[156:157], 0, v[144:145]
	v_lshl_add_u64 v[166:167], v[156:157], 0, v[2:3]
	v_lshl_add_u64 v[182:183], v[156:157], 0, v[150:151]
	v_lshl_add_u64 v[156:157], v[156:157], 0, v[146:147]
	v_lshl_add_u64 v[184:185], v[152:153], 0, v[144:145]
	v_lshl_add_u64 v[186:187], v[152:153], 0, v[2:3]
	v_lshl_add_u64 v[190:191], v[152:153], 0, v[150:151]
	v_lshl_add_u64 v[192:193], v[152:153], 0, v[146:147]
	global_load_dwordx2 v[194:195], v[158:159], off
	global_load_dwordx2 v[196:197], v[160:161], off
	global_load_dwordx2 v[168:169], v[162:163], off
; __device__ __forceinline__ float fast_rcp(float x) { return __builtin_amdgcn_rcpf(x); }
; __device__ __forceinline__ size_t g8_off(int row, int colg) { return ((size_t)(row >> 4) * 128 + (colg >> 5)) * 512 + (row & 15) * 32 + (colg & 31); }
;     __device__ __forceinline__ void hook(f32x4 (&acc)[2][2][4][2], const Unit& u, int nb, int wr, int wc, int fr, int fq) const {
;     ...
;                 for (int bj = 0; bj < 2; ++bj) { const int row = row0 + ai * 128 + m * 16, c = c0 + bj * 128;
;                     ga[m][bj] = *(const u32x2*)(G8 + g8_off(row, (nb - 1) * 1024 + c)); gb[m][bj] = *(const u32x2*)(G8 + g8_off(row, nb * 1024 + c)); }
; #pragma unroll
;             for (int m = 0; m < 4; ++m)
; #pragma unroll
;                 for (int bj = 0; bj < 2; ++bj)
; #pragma unroll
;                     for (int e = 0; e < 8; ++e) { const unsigned qa = ((e < 4 ? ga[m][bj].x : ga[m][bj].y) >> (8 * (e & 3))) & 255u, qb = ((e < 4 ? gb[m][bj].x : gb[m][bj].y) >> (8 * (e & 3))) & 255u;
;                         acc[ai][bj][m][e >> 2][e & 3] *= ((float)qa + 0.5f) * fast_rcp((float)qb + 0.5f); }
	global_load_dwordx2 v[170:171], v[154:155], off
	s_nop 0
	global_load_dwordx2 v[164:165], v[164:165], off
	s_nop 0
	global_load_dwordx2 v[166:167], v[166:167], off
	s_nop 0
	global_load_dwordx2 v[160:161], v[182:183], off
	global_load_dwordx2 v[162:163], v[156:157], off
	s_nop 0
	global_load_dwordx2 v[156:157], v[184:185], off
	global_load_dwordx2 v[158:159], v[186:187], off
	global_load_dwordx2 v[152:153], v[190:191], off
	global_load_dwordx2 v[154:155], v[192:193], off
	v_add_u32_e32 v200, 0x80, v1
	v_ashrrev_i32_e32 v200, 4, v200
	v_ashrrev_i32_e32 v201, 31, v200
	v_lshlrev_b64 v[200:201], 16, v[200:201]
	v_lshl_add_u64 v[200:201], v[148:149], 0, v[200:201]
	v_lshl_add_u64 v[202:203], v[200:201], 0, v[144:145]
	global_load_dwordx2 v[204:205], v[202:203], off
	v_lshl_add_u64 v[202:203], v[200:201], 0, v[2:3]
	global_load_dwordx2 v[206:207], v[202:203], off
	v_lshl_add_u64 v[202:203], v[200:201], 0, v[150:151]
	v_lshl_add_u64 v[200:201], v[200:201], 0, v[146:147]
	global_load_dwordx2 v[208:209], v[202:203], off
	global_load_dwordx2 v[210:211], v[200:201], off
	v_add_u32_e32 v200, 0x90, v1
	v_ashrrev_i32_e32 v200, 4, v200
	v_ashrrev_i32_e32 v201, 31, v200
	v_lshlrev_b64 v[200:201], 16, v[200:201]
	v_lshl_add_u64 v[200:201], v[148:149], 0, v[200:201]
	v_lshl_add_u64 v[202:203], v[200:201], 0, v[144:145]
	global_load_dwordx2 v[212:213], v[202:203], off
	v_lshl_add_u64 v[202:203], v[200:201], 0, v[2:3]
	global_load_dwordx2 v[214:215], v[202:203], off
	v_lshl_add_u64 v[202:203], v[200:201], 0, v[150:151]
	v_lshl_add_u64 v[200:201], v[200:201], 0, v[146:147]
	global_load_dwordx2 v[222:223], v[202:203], off
	global_load_dwordx2 v[224:225], v[200:201], off
	v_add_u32_e32 v200, 0xa0, v1
	v_add_u32_e32 v227, 0xb0, v1
	v_ashrrev_i32_e32 v200, 4, v200
	v_ashrrev_i32_e32 v228, 4, v227
	v_ashrrev_i32_e32 v201, 31, v200
	v_ashrrev_i32_e32 v229, 31, v228
	v_lshlrev_b64 v[200:201], 16, v[200:201]
	v_lshlrev_b64 v[228:229], 16, v[228:229]
	v_lshl_add_u64 v[202:203], v[148:149], 0, v[200:201]
	v_lshl_add_u64 v[230:231], v[148:149], 0, v[228:229]
	v_lshl_add_u64 v[200:201], v[202:203], 0, v[144:145]
	v_lshl_add_u64 v[232:233], v[230:231], 0, v[144:145]
	global_load_dwordx2 v[234:235], v[200:201], off
	global_load_dwordx2 v[236:237], v[232:233], off
	v_lshl_add_u64 v[200:201], v[202:203], 0, v[2:3]
	global_load_dwordx2 v[238:239], v[200:201], off
	v_lshl_add_u64 v[240:241], v[230:231], 0, v[2:3]
	global_load_dwordx2 v[228:229], v[240:241], off
	v_lshl_add_u64 v[240:241], v[230:231], 0, v[150:151]
	v_lshl_add_u64 v[232:233], v[230:231], 0, v[146:147]
	global_load_dwordx2 v[240:241], v[240:241], off
	global_load_dwordx2 v[232:233], v[232:233], off
	v_lshl_add_u64 v[200:201], v[202:203], 0, v[150:151]
	v_lshl_add_u64 v[202:203], v[202:203], 0, v[146:147]
	global_load_dwordx2 v[200:201], v[200:201], off
	s_nop 0
	global_load_dwordx2 v[202:203], v[202:203], off
	s_waitcnt vmcnt(16)
	v_cvt_f32_ubyte0_e32 v182, v172
	v_cvt_f32_ubyte1_e32 v183, v172
	v_add_f32_e32 v182, 0.5, v182
	v_add_f32_e32 v183, 0.5, v183
	v_rcp_f32_e32 v182, v182
	v_rcp_f32_e32 v183, v183
	v_cvt_f32_ubyte2_e32 v184, v172
	v_cvt_f32_ubyte3_e32 v172, v172
	v_add_f32_e32 v172, 0.5, v172
	v_rcp_f32_e32 v185, v172
	v_cvt_f32_ubyte0_e32 v172, v173
	v_add_f32_e32 v172, 0.5, v172
	v_add_f32_e32 v184, 0.5, v184
	v_rcp_f32_e32 v184, v184
	v_cvt_f32_ubyte1_e32 v187, v180
	v_cvt_f32_ubyte0_e32 v186, v180
	v_pk_add_f32 v[186:187], v[186:187], 0.5 op_sel_hi:[1,0]
	v_cvt_f32_ubyte3_e32 v191, v180
	v_pk_mul_f32 v[182:183], v[186:187], v[182:183]
	v_cvt_f32_ubyte2_e32 v190, v180
	v_pk_mul_f32 v[128:129], v[128:129], v[182:183]
	v_rcp_f32_e32 v182, v172
	v_cvt_f32_ubyte1_e32 v172, v173
	v_add_f32_e32 v172, 0.5, v172
	v_rcp_f32_e32 v183, v172
	v_cvt_f32_ubyte2_e32 v172, v173
	v_cvt_f32_ubyte3_e32 v173, v173
	v_add_f32_e32 v172, 0.5, v172
	v_add_f32_e32 v173, 0.5, v173
	v_rcp_f32_e32 v172, v172
	v_rcp_f32_e32 v173, v173
	v_pk_add_f32 v[190:191], v[190:191], 0.5 op_sel_hi:[1,0]
	v_cvt_f32_ubyte3_e32 v187, v181
	v_pk_mul_f32 v[184:185], v[190:191], v[184:185]
	v_cvt_f32_ubyte2_e32 v186, v181
	v_pk_mul_f32 v[130:131], v[130:131], v[184:185]
	v_cvt_f32_ubyte1_e32 v185, v181
	v_cvt_f32_ubyte0_e32 v184, v181
	v_pk_add_f32 v[180:181], v[186:187], 0.5 op_sel_hi:[1,0]
	v_pk_add_f32 v[184:185], v[184:185], 0.5 op_sel_hi:[1,0]
	v_pk_mul_f32 v[172:173], v[180:181], v[172:173]
	v_pk_mul_f32 v[182:183], v[184:185], v[182:183]
	v_pk_mul_f32 v[126:127], v[126:127], v[172:173]
	v_cvt_f32_ubyte0_e32 v172, v176
	v_cvt_f32_ubyte1_e32 v173, v176
	v_add_f32_e32 v172, 0.5, v172
	v_add_f32_e32 v173, 0.5, v173
	v_rcp_f32_e32 v172, v172
	v_rcp_f32_e32 v173, v173
	v_pk_mul_f32 v[124:125], v[124:125], v[182:183]
	v_cvt_f32_ubyte2_e32 v180, v176
	v_cvt_f32_ubyte3_e32 v176, v176
	v_cvt_f32_ubyte1_e32 v183, v174
	v_cvt_f32_ubyte0_e32 v182, v174
	v_add_f32_e32 v180, 0.5, v180
	v_add_f32_e32 v176, 0.5, v176
	v_pk_add_f32 v[182:183], v[182:183], 0.5 op_sel_hi:[1,0]
	v_rcp_f32_e32 v180, v180
	v_rcp_f32_e32 v181, v176
	v_pk_mul_f32 v[172:173], v[182:183], v[172:173]
	v_cvt_f32_ubyte3_e32 v185, v174
	v_pk_mul_f32 v[120:121], v[120:121], v[172:173]
	v_cvt_f32_ubyte0_e32 v172, v177
	v_cvt_f32_ubyte1_e32 v173, v177
	v_cvt_f32_ubyte2_e32 v184, v174
	v_add_f32_e32 v172, 0.5, v172
	v_add_f32_e32 v173, 0.5, v173
	v_pk_add_f32 v[184:185], v[184:185], 0.5 op_sel_hi:[1,0]
	v_rcp_f32_e32 v172, v172
	v_rcp_f32_e32 v173, v173
	v_pk_mul_f32 v[180:181], v[184:185], v[180:181]
	v_cvt_f32_ubyte2_e32 v174, v177
	v_pk_mul_f32 v[122:123], v[122:123], v[180:181]
	v_add_f32_e32 v174, 0.5, v174
	v_cvt_f32_ubyte1_e32 v181, v175
	v_cvt_f32_ubyte0_e32 v180, v175
; __device__ __forceinline__ float fast_rcp(float x) { return __builtin_amdgcn_rcpf(x); }
;     __device__ __forceinline__ void hook(f32x4 (&acc)[2][2][4][2], const Unit& u, int nb, int wr, int wc, int fr, int fq) const {
;     ...
; #pragma unroll
;             for (int m = 0; m < 4; ++m)
; #pragma unroll
;                 for (int bj = 0; bj < 2; ++bj)
; #pragma unroll
;                     for (int e = 0; e < 8; ++e) { const unsigned qa = ((e < 4 ? ga[m][bj].x : ga[m][bj].y) >> (8 * (e & 3))) & 255u, qb = ((e < 4 ? gb[m][bj].x : gb[m][bj].y) >> (8 * (e & 3))) & 255u;
;                         acc[ai][bj][m][e >> 2][e & 3] *= ((float)qa + 0.5f) * fast_rcp((float)qb + 0.5f); }
	v_rcp_f32_e32 v176, v174
	v_cvt_f32_ubyte3_e32 v174, v177
	v_pk_add_f32 v[180:181], v[180:181], 0.5 op_sel_hi:[1,0]
	v_add_f32_e32 v174, 0.5, v174
	v_pk_mul_f32 v[172:173], v[180:181], v[172:173]
	v_rcp_f32_e32 v177, v174
	v_pk_mul_f32 v[116:117], v[116:117], v[172:173]
	v_cvt_f32_ubyte0_e32 v172, v196
	v_cvt_f32_ubyte1_e32 v173, v196
	v_add_f32_e32 v172, 0.5, v172
	v_add_f32_e32 v173, 0.5, v173
	v_cvt_f32_ubyte3_e32 v183, v175
	v_cvt_f32_ubyte2_e32 v182, v175
	v_rcp_f32_e32 v172, v172
	v_rcp_f32_e32 v173, v173
	v_pk_add_f32 v[174:175], v[182:183], 0.5 op_sel_hi:[1,0]
	v_cvt_f32_ubyte3_e32 v181, v194
	v_pk_mul_f32 v[174:175], v[174:175], v[176:177]
	v_cvt_f32_ubyte1_e32 v177, v194
	v_cvt_f32_ubyte0_e32 v176, v194
	v_pk_add_f32 v[176:177], v[176:177], 0.5 op_sel_hi:[1,0]
	v_pk_mul_f32 v[118:119], v[118:119], v[174:175]
	v_cvt_f32_ubyte2_e32 v174, v196
	v_cvt_f32_ubyte3_e32 v175, v196
	v_pk_mul_f32 v[172:173], v[176:177], v[172:173]
	v_add_f32_e32 v174, 0.5, v174
	v_add_f32_e32 v175, 0.5, v175
	v_pk_mul_f32 v[112:113], v[112:113], v[172:173]
	v_cvt_f32_ubyte0_e32 v172, v197
	v_cvt_f32_ubyte1_e32 v173, v197
	v_rcp_f32_e32 v174, v174
	v_rcp_f32_e32 v175, v175
	v_add_f32_e32 v172, 0.5, v172
	v_add_f32_e32 v173, 0.5, v173
	v_rcp_f32_e32 v172, v172
	v_rcp_f32_e32 v173, v173
	v_cvt_f32_ubyte2_e32 v180, v194
	v_pk_add_f32 v[180:181], v[180:181], 0.5 op_sel_hi:[1,0]
	v_cvt_f32_ubyte1_e32 v177, v195
	v_cvt_f32_ubyte0_e32 v176, v195
	v_pk_mul_f32 v[174:175], v[180:181], v[174:175]
	v_pk_add_f32 v[176:177], v[176:177], 0.5 op_sel_hi:[1,0]
	v_pk_mul_f32 v[114:115], v[114:115], v[174:175]
	v_cvt_f32_ubyte2_e32 v174, v197
	v_cvt_f32_ubyte3_e32 v175, v197
	v_pk_mul_f32 v[172:173], v[176:177], v[172:173]
	v_add_f32_e32 v174, 0.5, v174
	v_add_f32_e32 v175, 0.5, v175
	v_pk_mul_f32 v[108:109], v[108:109], v[172:173]
	v_cvt_f32_ubyte0_e32 v172, v170
	v_cvt_f32_ubyte1_e32 v173, v170
	v_rcp_f32_e32 v174, v174
	v_rcp_f32_e32 v175, v175
	v_add_f32_e32 v172, 0.5, v172
	v_add_f32_e32 v173, 0.5, v173
	v_rcp_f32_e32 v172, v172
	v_rcp_f32_e32 v173, v173
	v_cvt_f32_ubyte3_e32 v181, v195
	v_cvt_f32_ubyte2_e32 v180, v195
	v_pk_add_f32 v[180:181], v[180:181], 0.5 op_sel_hi:[1,0]
	v_cvt_f32_ubyte1_e32 v177, v168
	v_cvt_f32_ubyte0_e32 v176, v168
	v_pk_mul_f32 v[174:175], v[180:181], v[174:175]
	v_cvt_f32_ubyte3_e32 v181, v168
	v_cvt_f32_ubyte2_e32 v180, v168
	v_pk_add_f32 v[176:177], v[176:177], 0.5 op_sel_hi:[1,0]
	v_cvt_f32_ubyte0_e32 v168, v171
	v_pk_mul_f32 v[172:173], v[176:177], v[172:173]
	v_add_f32_e32 v168, 0.5, v168
	v_pk_mul_f32 v[104:105], v[104:105], v[172:173]
	v_rcp_f32_e32 v172, v168
	v_cvt_f32_ubyte1_e32 v168, v171
	v_add_f32_e32 v168, 0.5, v168
	v_pk_mul_f32 v[110:111], v[110:111], v[174:175]
	v_cvt_f32_ubyte2_e32 v174, v170
	v_cvt_f32_ubyte3_e32 v170, v170
	v_rcp_f32_e32 v173, v168
	v_cvt_f32_ubyte2_e32 v168, v171
	v_add_f32_e32 v174, 0.5, v174
	v_add_f32_e32 v170, 0.5, v170
	v_add_f32_e32 v168, 0.5, v168
	v_rcp_f32_e32 v174, v174
	v_rcp_f32_e32 v175, v170
	v_rcp_f32_e32 v170, v168
	v_cvt_f32_ubyte3_e32 v168, v171
	v_add_f32_e32 v168, 0.5, v168
	v_rcp_f32_e32 v171, v168
	v_pk_add_f32 v[180:181], v[180:181], 0.5 op_sel_hi:[1,0]
	v_cvt_f32_ubyte3_e32 v177, v169
	v_pk_mul_f32 v[174:175], v[180:181], v[174:175]
	v_cvt_f32_ubyte2_e32 v176, v169
	v_pk_mul_f32 v[106:107], v[106:107], v[174:175]
	v_cvt_f32_ubyte1_e32 v175, v169
	v_cvt_f32_ubyte0_e32 v174, v169
	v_pk_add_f32 v[168:169], v[176:177], 0.5 op_sel_hi:[1,0]
	v_pk_add_f32 v[174:175], v[174:175], 0.5 op_sel_hi:[1,0]
	v_pk_mul_f32 v[168:169], v[168:169], v[170:171]
	v_pk_mul_f32 v[172:173], v[174:175], v[172:173]
	v_pk_mul_f32 v[102:103], v[102:103], v[168:169]
	v_cvt_f32_ubyte0_e32 v168, v166
	v_cvt_f32_ubyte1_e32 v169, v166
	v_add_f32_e32 v168, 0.5, v168
	v_add_f32_e32 v169, 0.5, v169
	v_rcp_f32_e32 v168, v168
	v_rcp_f32_e32 v169, v169
	v_pk_mul_f32 v[100:101], v[100:101], v[172:173]
	v_cvt_f32_ubyte1_e32 v173, v164
	v_cvt_f32_ubyte0_e32 v172, v164
	v_cvt_f32_ubyte3_e32 v175, v164
	v_cvt_f32_ubyte2_e32 v174, v164
	v_pk_add_f32 v[172:173], v[172:173], 0.5 op_sel_hi:[1,0]
	v_cvt_f32_ubyte0_e32 v164, v167
	v_pk_mul_f32 v[168:169], v[172:173], v[168:169]
	v_add_f32_e32 v164, 0.5, v164
	v_pk_mul_f32 v[96:97], v[96:97], v[168:169]
	v_rcp_f32_e32 v168, v164
	v_cvt_f32_ubyte1_e32 v164, v167
	v_add_f32_e32 v164, 0.5, v164
	v_cvt_f32_ubyte2_e32 v170, v166
	v_cvt_f32_ubyte3_e32 v166, v166
	v_rcp_f32_e32 v169, v164
	v_cvt_f32_ubyte2_e32 v164, v167
	v_add_f32_e32 v170, 0.5, v170
	v_add_f32_e32 v166, 0.5, v166
	v_add_f32_e32 v164, 0.5, v164
	v_rcp_f32_e32 v170, v170
	v_rcp_f32_e32 v171, v166
	v_rcp_f32_e32 v166, v164
	v_cvt_f32_ubyte3_e32 v164, v167
	v_add_f32_e32 v164, 0.5, v164
	v_rcp_f32_e32 v167, v164
	v_pk_add_f32 v[174:175], v[174:175], 0.5 op_sel_hi:[1,0]
	v_cvt_f32_ubyte3_e32 v173, v165
	v_pk_mul_f32 v[170:171], v[174:175], v[170:171]
	v_cvt_f32_ubyte2_e32 v172, v165
	v_pk_mul_f32 v[98:99], v[98:99], v[170:171]
	v_cvt_f32_ubyte1_e32 v171, v165
	v_cvt_f32_ubyte0_e32 v170, v165
	v_pk_add_f32 v[164:165], v[172:173], 0.5 op_sel_hi:[1,0]
	v_pk_add_f32 v[170:171], v[170:171], 0.5 op_sel_hi:[1,0]
	v_pk_mul_f32 v[164:165], v[164:165], v[166:167]
	v_pk_mul_f32 v[168:169], v[170:171], v[168:169]
	v_pk_mul_f32 v[94:95], v[94:95], v[164:165]
	v_cvt_f32_ubyte0_e32 v164, v162
	v_cvt_f32_ubyte1_e32 v165, v162
	v_add_f32_e32 v164, 0.5, v164
	v_add_f32_e32 v165, 0.5, v165
	v_rcp_f32_e32 v164, v164
	v_rcp_f32_e32 v165, v165
	v_pk_mul_f32 v[92:93], v[92:93], v[168:169]
	v_cvt_f32_ubyte1_e32 v169, v160
	v_cvt_f32_ubyte0_e32 v168, v160
	v_cvt_f32_ubyte3_e32 v171, v160
	v_cvt_f32_ubyte2_e32 v170, v160
; __device__ __forceinline__ float fast_rcp(float x) { return __builtin_amdgcn_rcpf(x); }
; __device__ __forceinline__ size_t g8_off(int row, int colg) { return ((size_t)(row >> 4) * 128 + (colg >> 5)) * 512 + (row & 15) * 32 + (colg & 31); }
;     __device__ __forceinline__ void hook(f32x4 (&acc)[2][2][4][2], const Unit& u, int nb, int wr, int wc, int fr, int fq) const {
;     ...
;         for (int ai = 0; ai < 2; ++ai) {
;             u32x2 ga[4][2], gb[4][2];
; #pragma unroll
;             for (int m = 0; m < 4; ++m)
; #pragma unroll
;                 for (int bj = 0; bj < 2; ++bj) { const int row = row0 + ai * 128 + m * 16, c = c0 + bj * 128;
;                     ga[m][bj] = *(const u32x2*)(G8 + g8_off(row, (nb - 1) * 1024 + c)); gb[m][bj] = *(const u32x2*)(G8 + g8_off(row, nb * 1024 + c)); }
; #pragma unroll
;             for (int m = 0; m < 4; ++m)
; #pragma unroll
;                 for (int bj = 0; bj < 2; ++bj)
; #pragma unroll
;                     for (int e = 0; e < 8; ++e) { const unsigned qa = ((e < 4 ? ga[m][bj].x : ga[m][bj].y) >> (8 * (e & 3))) & 255u, qb = ((e < 4 ? gb[m][bj].x : gb[m][bj].y) >> (8 * (e & 3))) & 255u;
;                         acc[ai][bj][m][e >> 2][e & 3] *= ((float)qa + 0.5f) * fast_rcp((float)qb + 0.5f); }
	v_pk_add_f32 v[168:169], v[168:169], 0.5 op_sel_hi:[1,0]
	v_cvt_f32_ubyte0_e32 v160, v163
	v_pk_mul_f32 v[164:165], v[168:169], v[164:165]
	v_add_f32_e32 v160, 0.5, v160
	v_pk_mul_f32 v[88:89], v[88:89], v[164:165]
	v_rcp_f32_e32 v164, v160
	v_cvt_f32_ubyte1_e32 v160, v163
	v_add_f32_e32 v160, 0.5, v160
	v_cvt_f32_ubyte2_e32 v166, v162
	v_cvt_f32_ubyte3_e32 v162, v162
	v_rcp_f32_e32 v165, v160
	v_cvt_f32_ubyte2_e32 v160, v163
	v_add_f32_e32 v166, 0.5, v166
	v_add_f32_e32 v162, 0.5, v162
	v_add_f32_e32 v160, 0.5, v160
	v_rcp_f32_e32 v166, v166
	v_rcp_f32_e32 v167, v162
	v_rcp_f32_e32 v162, v160
	v_cvt_f32_ubyte3_e32 v160, v163
	v_add_f32_e32 v160, 0.5, v160
	v_rcp_f32_e32 v163, v160
	v_pk_add_f32 v[170:171], v[170:171], 0.5 op_sel_hi:[1,0]
	v_cvt_f32_ubyte3_e32 v169, v161
	v_pk_mul_f32 v[166:167], v[170:171], v[166:167]
	v_cvt_f32_ubyte2_e32 v168, v161
	v_pk_mul_f32 v[90:91], v[90:91], v[166:167]
	v_cvt_f32_ubyte1_e32 v167, v161
	v_cvt_f32_ubyte0_e32 v166, v161
	v_pk_add_f32 v[160:161], v[168:169], 0.5 op_sel_hi:[1,0]
	v_pk_add_f32 v[166:167], v[166:167], 0.5 op_sel_hi:[1,0]
	v_pk_mul_f32 v[160:161], v[160:161], v[162:163]
	v_pk_mul_f32 v[164:165], v[166:167], v[164:165]
	v_pk_mul_f32 v[86:87], v[86:87], v[160:161]
	v_cvt_f32_ubyte0_e32 v160, v158
	v_cvt_f32_ubyte1_e32 v161, v158
	v_add_f32_e32 v160, 0.5, v160
	v_add_f32_e32 v161, 0.5, v161
	v_rcp_f32_e32 v160, v160
	v_rcp_f32_e32 v161, v161
	v_pk_mul_f32 v[84:85], v[84:85], v[164:165]
	v_cvt_f32_ubyte1_e32 v165, v156
	v_cvt_f32_ubyte0_e32 v164, v156
	v_cvt_f32_ubyte3_e32 v167, v156
	v_cvt_f32_ubyte2_e32 v166, v156
	v_pk_add_f32 v[164:165], v[164:165], 0.5 op_sel_hi:[1,0]
	v_cvt_f32_ubyte0_e32 v156, v159
	v_pk_mul_f32 v[160:161], v[164:165], v[160:161]
	v_add_f32_e32 v156, 0.5, v156
	v_pk_mul_f32 v[80:81], v[80:81], v[160:161]
	v_rcp_f32_e32 v160, v156
	v_cvt_f32_ubyte1_e32 v156, v159
	v_add_f32_e32 v156, 0.5, v156
	v_cvt_f32_ubyte2_e32 v162, v158
	v_cvt_f32_ubyte3_e32 v158, v158
	v_rcp_f32_e32 v161, v156
	v_cvt_f32_ubyte2_e32 v156, v159
	v_add_f32_e32 v162, 0.5, v162
	v_add_f32_e32 v158, 0.5, v158
	v_add_f32_e32 v156, 0.5, v156
	v_rcp_f32_e32 v162, v162
	v_rcp_f32_e32 v163, v158
	v_rcp_f32_e32 v158, v156
	v_cvt_f32_ubyte3_e32 v156, v159
	v_add_f32_e32 v156, 0.5, v156
	v_rcp_f32_e32 v159, v156
	v_pk_add_f32 v[166:167], v[166:167], 0.5 op_sel_hi:[1,0]
	v_cvt_f32_ubyte3_e32 v165, v157
	v_pk_mul_f32 v[162:163], v[166:167], v[162:163]
	v_cvt_f32_ubyte2_e32 v164, v157
	v_pk_mul_f32 v[82:83], v[82:83], v[162:163]
	v_cvt_f32_ubyte1_e32 v163, v157
	v_cvt_f32_ubyte0_e32 v162, v157
	v_pk_add_f32 v[156:157], v[164:165], 0.5 op_sel_hi:[1,0]
	v_pk_add_f32 v[162:163], v[162:163], 0.5 op_sel_hi:[1,0]
	v_pk_mul_f32 v[156:157], v[156:157], v[158:159]
	v_pk_mul_f32 v[160:161], v[162:163], v[160:161]
	v_pk_mul_f32 v[78:79], v[78:79], v[156:157]
	v_cvt_f32_ubyte0_e32 v156, v154
	v_cvt_f32_ubyte1_e32 v157, v154
	v_add_f32_e32 v156, 0.5, v156
	v_add_f32_e32 v157, 0.5, v157
	v_rcp_f32_e32 v156, v156
	v_rcp_f32_e32 v157, v157
	v_pk_mul_f32 v[76:77], v[76:77], v[160:161]
	v_cvt_f32_ubyte1_e32 v161, v152
	v_cvt_f32_ubyte0_e32 v160, v152
	v_cvt_f32_ubyte3_e32 v163, v152
	v_cvt_f32_ubyte2_e32 v162, v152
	v_pk_add_f32 v[160:161], v[160:161], 0.5 op_sel_hi:[1,0]
	v_cvt_f32_ubyte0_e32 v152, v155
	v_pk_mul_f32 v[156:157], v[160:161], v[156:157]
	v_add_f32_e32 v152, 0.5, v152
	v_pk_mul_f32 v[72:73], v[72:73], v[156:157]
	v_rcp_f32_e32 v156, v152
	v_cvt_f32_ubyte1_e32 v152, v155
	v_cvt_f32_ubyte2_e32 v158, v154
	v_cvt_f32_ubyte3_e32 v154, v154
	v_add_f32_e32 v152, 0.5, v152
	v_add_f32_e32 v158, 0.5, v158
	v_add_f32_e32 v154, 0.5, v154
	v_rcp_f32_e32 v157, v152
	v_cvt_f32_ubyte2_e32 v152, v155
	v_rcp_f32_e32 v158, v158
	v_rcp_f32_e32 v159, v154
	v_add_f32_e32 v152, 0.5, v152
	v_rcp_f32_e32 v154, v152
	v_cvt_f32_ubyte3_e32 v152, v155
	v_add_f32_e32 v152, 0.5, v152
	v_pk_add_f32 v[162:163], v[162:163], 0.5 op_sel_hi:[1,0]
	v_rcp_f32_e32 v155, v152
	v_pk_mul_f32 v[158:159], v[162:163], v[158:159]
	v_cvt_f32_ubyte3_e32 v161, v153
	v_pk_mul_f32 v[74:75], v[74:75], v[158:159]
	v_cvt_f32_ubyte1_e32 v159, v153
	v_cvt_f32_ubyte0_e32 v158, v153
	v_cvt_f32_ubyte2_e32 v160, v153
	v_pk_add_f32 v[152:153], v[160:161], 0.5 op_sel_hi:[1,0]
	v_pk_add_f32 v[158:159], v[158:159], 0.5 op_sel_hi:[1,0]
	v_pk_mul_f32 v[152:153], v[152:153], v[154:155]
	v_pk_mul_f32 v[156:157], v[158:159], v[156:157]
	v_pk_mul_f32 v[70:71], v[70:71], v[152:153]
	v_pk_mul_f32 v[68:69], v[68:69], v[156:157]
	s_waitcnt vmcnt(0)
; __device__ __forceinline__ float fast_rcp(float x) { return __builtin_amdgcn_rcpf(x); }
;     __device__ __forceinline__ void hook(f32x4 (&acc)[2][2][4][2], const Unit& u, int nb, int wr, int wc, int fr, int fq) const {
;     ...
; #pragma unroll
;             for (int m = 0; m < 4; ++m)
; #pragma unroll
;                 for (int bj = 0; bj < 2; ++bj)
; #pragma unroll
;                     for (int e = 0; e < 8; ++e) { const unsigned qa = ((e < 4 ? ga[m][bj].x : ga[m][bj].y) >> (8 * (e & 3))) & 255u, qb = ((e < 4 ? gb[m][bj].x : gb[m][bj].y) >> (8 * (e & 3))) & 255u;
;                         acc[ai][bj][m][e >> 2][e & 3] *= ((float)qa + 0.5f) * fast_rcp((float)qb + 0.5f); }
	v_mov_b64_e32 v[174:175], v[204:205]
	v_mov_b64_e32 v[176:177], v[206:207]
	v_mov_b64_e32 v[170:171], v[208:209]
	v_mov_b64_e32 v[172:173], v[210:211]
	v_mov_b64_e32 v[166:167], v[212:213]
	v_mov_b64_e32 v[168:169], v[214:215]
	v_mov_b64_e32 v[162:163], v[222:223]
	v_mov_b64_e32 v[164:165], v[224:225]
	v_mov_b64_e32 v[156:157], v[234:235]
	v_mov_b64_e32 v[148:149], v[236:237]
	v_mov_b64_e32 v[158:159], v[238:239]
	v_mov_b64_e32 v[160:161], v[228:229]
	v_mov_b64_e32 v[2:3], v[240:241]
	v_mov_b64_e32 v[144:145], v[232:233]
	v_mov_b64_e32 v[152:153], v[200:201]
	v_mov_b64_e32 v[154:155], v[202:203]
	v_cvt_f32_ubyte1_e32 v181, v174
	v_cvt_f32_ubyte0_e32 v1, v176
	v_add_f32_e32 v1, 0.5, v1
	v_rcp_f32_e32 v146, v1
	v_cvt_f32_ubyte1_e32 v1, v176
	v_add_f32_e32 v1, 0.5, v1
	v_rcp_f32_e32 v147, v1
	v_cvt_f32_ubyte2_e32 v1, v176
	v_add_f32_e32 v1, 0.5, v1
	v_rcp_f32_e32 v150, v1
	v_cvt_f32_ubyte3_e32 v1, v176
	v_add_f32_e32 v1, 0.5, v1
	v_cvt_f32_ubyte0_e32 v180, v174
	v_rcp_f32_e32 v151, v1
	v_pk_add_f32 v[180:181], v[180:181], 0.5 op_sel_hi:[1,0]
	v_cvt_f32_ubyte0_e32 v1, v177
	v_pk_mul_f32 v[146:147], v[180:181], v[146:147]
	v_add_f32_e32 v1, 0.5, v1
	v_pk_mul_f32 v[64:65], v[64:65], v[146:147]
	v_rcp_f32_e32 v146, v1
	v_cvt_f32_ubyte1_e32 v1, v177
	v_cvt_f32_ubyte3_e32 v183, v174
	v_cvt_f32_ubyte2_e32 v182, v174
	v_add_f32_e32 v1, 0.5, v1
	v_pk_add_f32 v[182:183], v[182:183], 0.5 op_sel_hi:[1,0]
	v_rcp_f32_e32 v147, v1
	v_cvt_f32_ubyte2_e32 v1, v177
	v_pk_mul_f32 v[150:151], v[182:183], v[150:151]
	v_add_f32_e32 v1, 0.5, v1
	v_pk_mul_f32 v[66:67], v[66:67], v[150:151]
	v_rcp_f32_e32 v150, v1
	v_cvt_f32_ubyte3_e32 v1, v177
	v_add_f32_e32 v1, 0.5, v1
	v_cvt_f32_ubyte1_e32 v177, v175
	v_cvt_f32_ubyte0_e32 v176, v175
	v_rcp_f32_e32 v151, v1
	v_pk_add_f32 v[176:177], v[176:177], 0.5 op_sel_hi:[1,0]
	v_cvt_f32_ubyte0_e32 v1, v172
	v_pk_mul_f32 v[146:147], v[176:177], v[146:147]
	v_add_f32_e32 v1, 0.5, v1
	v_pk_mul_f32 v[60:61], v[60:61], v[146:147]
	v_rcp_f32_e32 v146, v1
	v_cvt_f32_ubyte1_e32 v1, v172
	v_cvt_f32_ubyte3_e32 v181, v175
	v_cvt_f32_ubyte2_e32 v180, v175
	v_add_f32_e32 v1, 0.5, v1
	v_pk_add_f32 v[174:175], v[180:181], 0.5 op_sel_hi:[1,0]
	v_rcp_f32_e32 v147, v1
	v_cvt_f32_ubyte2_e32 v1, v172
	v_pk_mul_f32 v[150:151], v[174:175], v[150:151]
	v_add_f32_e32 v1, 0.5, v1
	v_pk_mul_f32 v[62:63], v[62:63], v[150:151]
	v_rcp_f32_e32 v150, v1
	v_cvt_f32_ubyte3_e32 v1, v172
	v_add_f32_e32 v1, 0.5, v1
	v_cvt_f32_ubyte1_e32 v175, v170
	v_cvt_f32_ubyte0_e32 v174, v170
	v_rcp_f32_e32 v151, v1
	v_pk_add_f32 v[174:175], v[174:175], 0.5 op_sel_hi:[1,0]
	v_cvt_f32_ubyte0_e32 v1, v173
	v_pk_mul_f32 v[146:147], v[174:175], v[146:147]
	v_add_f32_e32 v1, 0.5, v1
	v_pk_mul_f32 v[56:57], v[56:57], v[146:147]
	v_rcp_f32_e32 v146, v1
	v_cvt_f32_ubyte1_e32 v1, v173
	v_cvt_f32_ubyte3_e32 v177, v170
	v_cvt_f32_ubyte2_e32 v176, v170
	v_add_f32_e32 v1, 0.5, v1
	v_pk_add_f32 v[176:177], v[176:177], 0.5 op_sel_hi:[1,0]
	v_rcp_f32_e32 v147, v1
	v_cvt_f32_ubyte2_e32 v1, v173
	v_pk_mul_f32 v[150:151], v[176:177], v[150:151]
	v_add_f32_e32 v1, 0.5, v1
	v_pk_mul_f32 v[58:59], v[58:59], v[150:151]
	v_rcp_f32_e32 v150, v1
	v_cvt_f32_ubyte3_e32 v1, v173
	v_add_f32_e32 v1, 0.5, v1
	v_cvt_f32_ubyte1_e32 v173, v171
	v_cvt_f32_ubyte0_e32 v172, v171
	v_rcp_f32_e32 v151, v1
	v_pk_add_f32 v[172:173], v[172:173], 0.5 op_sel_hi:[1,0]
	v_cvt_f32_ubyte0_e32 v1, v168
	v_pk_mul_f32 v[146:147], v[172:173], v[146:147]
	v_add_f32_e32 v1, 0.5, v1
	v_pk_mul_f32 v[52:53], v[52:53], v[146:147]
	v_rcp_f32_e32 v146, v1
	v_cvt_f32_ubyte1_e32 v1, v168
	v_cvt_f32_ubyte3_e32 v175, v171
	v_cvt_f32_ubyte2_e32 v174, v171
	v_add_f32_e32 v1, 0.5, v1
	v_pk_add_f32 v[170:171], v[174:175], 0.5 op_sel_hi:[1,0]
	v_rcp_f32_e32 v147, v1
	v_cvt_f32_ubyte2_e32 v1, v168
	v_pk_mul_f32 v[150:151], v[170:171], v[150:151]
	v_add_f32_e32 v1, 0.5, v1
	v_pk_mul_f32 v[54:55], v[54:55], v[150:151]
	v_rcp_f32_e32 v150, v1
	v_cvt_f32_ubyte3_e32 v1, v168
	v_add_f32_e32 v1, 0.5, v1
	v_cvt_f32_ubyte1_e32 v171, v166
	v_cvt_f32_ubyte0_e32 v170, v166
	v_rcp_f32_e32 v151, v1
	v_pk_add_f32 v[170:171], v[170:171], 0.5 op_sel_hi:[1,0]
	v_cvt_f32_ubyte0_e32 v1, v169
	v_pk_mul_f32 v[146:147], v[170:171], v[146:147]
	v_add_f32_e32 v1, 0.5, v1
	v_pk_mul_f32 v[48:49], v[48:49], v[146:147]
	v_rcp_f32_e32 v146, v1
	v_cvt_f32_ubyte1_e32 v1, v169
	v_cvt_f32_ubyte3_e32 v173, v166
	v_cvt_f32_ubyte2_e32 v172, v166
	v_add_f32_e32 v1, 0.5, v1
	v_pk_add_f32 v[172:173], v[172:173], 0.5 op_sel_hi:[1,0]
	v_rcp_f32_e32 v147, v1
	v_cvt_f32_ubyte2_e32 v1, v169
	v_pk_mul_f32 v[150:151], v[172:173], v[150:151]
	v_add_f32_e32 v1, 0.5, v1
	v_pk_mul_f32 v[50:51], v[50:51], v[150:151]
	v_rcp_f32_e32 v150, v1
	v_cvt_f32_ubyte3_e32 v1, v169
	v_add_f32_e32 v1, 0.5, v1
	v_cvt_f32_ubyte1_e32 v169, v167
	v_cvt_f32_ubyte0_e32 v168, v167
	v_rcp_f32_e32 v151, v1
	v_pk_add_f32 v[168:169], v[168:169], 0.5 op_sel_hi:[1,0]
	v_cvt_f32_ubyte0_e32 v1, v164
	v_pk_mul_f32 v[146:147], v[168:169], v[146:147]
	v_add_f32_e32 v1, 0.5, v1
	v_pk_mul_f32 v[44:45], v[44:45], v[146:147]
	v_rcp_f32_e32 v146, v1
	v_cvt_f32_ubyte1_e32 v1, v164
	v_cvt_f32_ubyte3_e32 v171, v167
	v_cvt_f32_ubyte2_e32 v170, v167
	v_add_f32_e32 v1, 0.5, v1
	v_pk_add_f32 v[166:167], v[170:171], 0.5 op_sel_hi:[1,0]
	v_rcp_f32_e32 v147, v1
	v_cvt_f32_ubyte2_e32 v1, v164
	v_pk_mul_f32 v[150:151], v[166:167], v[150:151]
	v_add_f32_e32 v1, 0.5, v1
	v_pk_mul_f32 v[46:47], v[46:47], v[150:151]
	v_rcp_f32_e32 v150, v1
	v_cvt_f32_ubyte3_e32 v1, v164
	v_add_f32_e32 v1, 0.5, v1
	v_cvt_f32_ubyte1_e32 v167, v162
	v_cvt_f32_ubyte0_e32 v166, v162
	v_rcp_f32_e32 v151, v1
	v_pk_add_f32 v[166:167], v[166:167], 0.5 op_sel_hi:[1,0]
; __device__ __forceinline__ float fast_rcp(float x) { return __builtin_amdgcn_rcpf(x); }
;     __device__ __forceinline__ void hook(f32x4 (&acc)[2][2][4][2], const Unit& u, int nb, int wr, int wc, int fr, int fq) const {
;     ...
; #pragma unroll
;             for (int m = 0; m < 4; ++m)
; #pragma unroll
;                 for (int bj = 0; bj < 2; ++bj)
; #pragma unroll
;                     for (int e = 0; e < 8; ++e) { const unsigned qa = ((e < 4 ? ga[m][bj].x : ga[m][bj].y) >> (8 * (e & 3))) & 255u, qb = ((e < 4 ? gb[m][bj].x : gb[m][bj].y) >> (8 * (e & 3))) & 255u;
;                         acc[ai][bj][m][e >> 2][e & 3] *= ((float)qa + 0.5f) * fast_rcp((float)qb + 0.5f); }
	v_cvt_f32_ubyte0_e32 v1, v165
	v_pk_mul_f32 v[146:147], v[166:167], v[146:147]
	v_add_f32_e32 v1, 0.5, v1
	v_pk_mul_f32 v[40:41], v[40:41], v[146:147]
	v_rcp_f32_e32 v146, v1
	v_cvt_f32_ubyte1_e32 v1, v165
	v_cvt_f32_ubyte3_e32 v169, v162
	v_cvt_f32_ubyte2_e32 v168, v162
	v_add_f32_e32 v1, 0.5, v1
	v_pk_add_f32 v[168:169], v[168:169], 0.5 op_sel_hi:[1,0]
	v_rcp_f32_e32 v147, v1
	v_cvt_f32_ubyte2_e32 v1, v165
	v_pk_mul_f32 v[150:151], v[168:169], v[150:151]
	v_add_f32_e32 v1, 0.5, v1
	v_pk_mul_f32 v[42:43], v[42:43], v[150:151]
	v_rcp_f32_e32 v150, v1
	v_cvt_f32_ubyte3_e32 v1, v165
	v_add_f32_e32 v1, 0.5, v1
	v_cvt_f32_ubyte1_e32 v165, v163
	v_cvt_f32_ubyte0_e32 v164, v163
	v_rcp_f32_e32 v151, v1
	v_pk_add_f32 v[164:165], v[164:165], 0.5 op_sel_hi:[1,0]
	v_cvt_f32_ubyte0_e32 v1, v158
	v_pk_mul_f32 v[146:147], v[164:165], v[146:147]
	v_add_f32_e32 v1, 0.5, v1
	v_pk_mul_f32 v[36:37], v[36:37], v[146:147]
	v_rcp_f32_e32 v146, v1
	v_cvt_f32_ubyte1_e32 v1, v158
	v_cvt_f32_ubyte3_e32 v167, v163
	v_cvt_f32_ubyte2_e32 v166, v163
	v_add_f32_e32 v1, 0.5, v1
	v_pk_add_f32 v[162:163], v[166:167], 0.5 op_sel_hi:[1,0]
	v_rcp_f32_e32 v147, v1
	v_cvt_f32_ubyte2_e32 v1, v158
	v_pk_mul_f32 v[150:151], v[162:163], v[150:151]
	v_add_f32_e32 v1, 0.5, v1
	v_pk_mul_f32 v[38:39], v[38:39], v[150:151]
	v_rcp_f32_e32 v150, v1
	v_cvt_f32_ubyte3_e32 v1, v158
	v_add_f32_e32 v1, 0.5, v1
	v_cvt_f32_ubyte1_e32 v163, v156
	v_cvt_f32_ubyte0_e32 v162, v156
	v_rcp_f32_e32 v151, v1
	v_pk_add_f32 v[162:163], v[162:163], 0.5 op_sel_hi:[1,0]
	v_cvt_f32_ubyte0_e32 v1, v159
	v_pk_mul_f32 v[146:147], v[162:163], v[146:147]
	v_add_f32_e32 v1, 0.5, v1
	v_pk_mul_f32 v[32:33], v[32:33], v[146:147]
	v_rcp_f32_e32 v146, v1
	v_cvt_f32_ubyte1_e32 v1, v159
	v_cvt_f32_ubyte3_e32 v165, v156
	v_cvt_f32_ubyte2_e32 v164, v156
	v_add_f32_e32 v1, 0.5, v1
	v_pk_add_f32 v[164:165], v[164:165], 0.5 op_sel_hi:[1,0]
	v_rcp_f32_e32 v147, v1
	v_cvt_f32_ubyte2_e32 v1, v159
	v_pk_mul_f32 v[150:151], v[164:165], v[150:151]
	v_add_f32_e32 v1, 0.5, v1
	v_pk_mul_f32 v[34:35], v[34:35], v[150:151]
	v_rcp_f32_e32 v150, v1
	v_cvt_f32_ubyte3_e32 v1, v159
	v_add_f32_e32 v1, 0.5, v1
	v_cvt_f32_ubyte1_e32 v159, v157
	v_cvt_f32_ubyte0_e32 v158, v157
	v_rcp_f32_e32 v151, v1
	v_pk_add_f32 v[158:159], v[158:159], 0.5 op_sel_hi:[1,0]
	s_waitcnt vmcnt(0)
; __device__ __forceinline__ float fast_rcp(float x) { return __builtin_amdgcn_rcpf(x); }
;     __device__ __forceinline__ void hook(f32x4 (&acc)[2][2][4][2], const Unit& u, int nb, int wr, int wc, int fr, int fq) const {
;     ...
; #pragma unroll
;             for (int m = 0; m < 4; ++m)
; #pragma unroll
;                 for (int bj = 0; bj < 2; ++bj)
; #pragma unroll
;                     for (int e = 0; e < 8; ++e) { const unsigned qa = ((e < 4 ? ga[m][bj].x : ga[m][bj].y) >> (8 * (e & 3))) & 255u, qb = ((e < 4 ? gb[m][bj].x : gb[m][bj].y) >> (8 * (e & 3))) & 255u;
;                         acc[ai][bj][m][e >> 2][e & 3] *= ((float)qa + 0.5f) * fast_rcp((float)qb + 0.5f); }
;             __builtin_amdgcn_sched_barrier(0);
	v_cvt_f32_ubyte0_e32 v1, v154
	v_pk_mul_f32 v[146:147], v[158:159], v[146:147]
	v_add_f32_e32 v1, 0.5, v1
	v_pk_mul_f32 v[28:29], v[28:29], v[146:147]
	v_rcp_f32_e32 v146, v1
	v_cvt_f32_ubyte1_e32 v1, v154
	v_cvt_f32_ubyte3_e32 v163, v157
	v_cvt_f32_ubyte2_e32 v162, v157
	v_add_f32_e32 v1, 0.5, v1
	v_pk_add_f32 v[156:157], v[162:163], 0.5 op_sel_hi:[1,0]
	v_rcp_f32_e32 v147, v1
	v_cvt_f32_ubyte2_e32 v1, v154
	v_pk_mul_f32 v[150:151], v[156:157], v[150:151]
	v_add_f32_e32 v1, 0.5, v1
	v_pk_mul_f32 v[30:31], v[30:31], v[150:151]
	v_rcp_f32_e32 v150, v1
	v_cvt_f32_ubyte3_e32 v1, v154
	v_add_f32_e32 v1, 0.5, v1
	v_cvt_f32_ubyte1_e32 v157, v152
	v_cvt_f32_ubyte0_e32 v156, v152
	v_rcp_f32_e32 v151, v1
	v_pk_add_f32 v[156:157], v[156:157], 0.5 op_sel_hi:[1,0]
	v_cvt_f32_ubyte0_e32 v1, v155
	v_pk_mul_f32 v[146:147], v[156:157], v[146:147]
	v_add_f32_e32 v1, 0.5, v1
	v_pk_mul_f32 v[24:25], v[24:25], v[146:147]
	v_rcp_f32_e32 v146, v1
	v_cvt_f32_ubyte1_e32 v1, v155
	v_cvt_f32_ubyte3_e32 v159, v152
	v_cvt_f32_ubyte2_e32 v158, v152
	v_add_f32_e32 v1, 0.5, v1
	v_pk_add_f32 v[158:159], v[158:159], 0.5 op_sel_hi:[1,0]
	v_rcp_f32_e32 v147, v1
	v_cvt_f32_ubyte2_e32 v1, v155
	v_pk_mul_f32 v[150:151], v[158:159], v[150:151]
	v_add_f32_e32 v1, 0.5, v1
	v_pk_mul_f32 v[26:27], v[26:27], v[150:151]
	v_rcp_f32_e32 v150, v1
	v_cvt_f32_ubyte3_e32 v1, v155
	v_add_f32_e32 v1, 0.5, v1
	v_cvt_f32_ubyte1_e32 v155, v153
	v_cvt_f32_ubyte0_e32 v154, v153
	v_rcp_f32_e32 v151, v1
	v_pk_add_f32 v[154:155], v[154:155], 0.5 op_sel_hi:[1,0]
	v_cvt_f32_ubyte0_e32 v1, v160
	v_pk_mul_f32 v[146:147], v[154:155], v[146:147]
	v_add_f32_e32 v1, 0.5, v1
	v_pk_mul_f32 v[20:21], v[20:21], v[146:147]
	v_rcp_f32_e32 v146, v1
	v_cvt_f32_ubyte1_e32 v1, v160
	v_cvt_f32_ubyte3_e32 v157, v153
	v_cvt_f32_ubyte2_e32 v156, v153
	v_add_f32_e32 v1, 0.5, v1
	v_pk_add_f32 v[152:153], v[156:157], 0.5 op_sel_hi:[1,0]
	v_rcp_f32_e32 v147, v1
	v_cvt_f32_ubyte2_e32 v1, v160
	v_pk_mul_f32 v[150:151], v[152:153], v[150:151]
	v_add_f32_e32 v1, 0.5, v1
	v_pk_mul_f32 v[22:23], v[22:23], v[150:151]
	v_rcp_f32_e32 v150, v1
	v_cvt_f32_ubyte3_e32 v1, v160
	v_add_f32_e32 v1, 0.5, v1
	v_cvt_f32_ubyte1_e32 v153, v148
	v_cvt_f32_ubyte0_e32 v152, v148
	v_rcp_f32_e32 v151, v1
	v_pk_add_f32 v[152:153], v[152:153], 0.5 op_sel_hi:[1,0]
	v_cvt_f32_ubyte0_e32 v1, v161
	v_pk_mul_f32 v[146:147], v[152:153], v[146:147]
	v_add_f32_e32 v1, 0.5, v1
	v_pk_mul_f32 v[16:17], v[16:17], v[146:147]
	v_rcp_f32_e32 v146, v1
	v_cvt_f32_ubyte1_e32 v1, v161
	v_cvt_f32_ubyte3_e32 v155, v148
	v_cvt_f32_ubyte2_e32 v154, v148
	v_add_f32_e32 v1, 0.5, v1
	v_pk_add_f32 v[154:155], v[154:155], 0.5 op_sel_hi:[1,0]
	v_rcp_f32_e32 v147, v1
	v_cvt_f32_ubyte2_e32 v1, v161
	v_pk_mul_f32 v[150:151], v[154:155], v[150:151]
	v_add_f32_e32 v1, 0.5, v1
	v_pk_mul_f32 v[18:19], v[18:19], v[150:151]
	v_rcp_f32_e32 v150, v1
	v_cvt_f32_ubyte3_e32 v1, v161
	v_add_f32_e32 v1, 0.5, v1
	v_cvt_f32_ubyte1_e32 v153, v149
	v_cvt_f32_ubyte0_e32 v152, v149
	v_rcp_f32_e32 v151, v1
	v_pk_add_f32 v[152:153], v[152:153], 0.5 op_sel_hi:[1,0]
	v_cvt_f32_ubyte0_e32 v1, v144
	v_pk_mul_f32 v[146:147], v[152:153], v[146:147]
	v_add_f32_e32 v1, 0.5, v1
	v_pk_mul_f32 v[12:13], v[12:13], v[146:147]
	v_rcp_f32_e32 v146, v1
	v_cvt_f32_ubyte1_e32 v1, v144
	v_cvt_f32_ubyte3_e32 v155, v149
	v_cvt_f32_ubyte2_e32 v154, v149
	v_add_f32_e32 v1, 0.5, v1
	v_pk_add_f32 v[148:149], v[154:155], 0.5 op_sel_hi:[1,0]
	v_rcp_f32_e32 v147, v1
	v_cvt_f32_ubyte2_e32 v1, v144
	v_pk_mul_f32 v[148:149], v[148:149], v[150:151]
	v_add_f32_e32 v1, 0.5, v1
	v_pk_mul_f32 v[14:15], v[14:15], v[148:149]
	v_rcp_f32_e32 v148, v1
	v_cvt_f32_ubyte3_e32 v1, v144
	v_add_f32_e32 v1, 0.5, v1
	v_cvt_f32_ubyte1_e32 v151, v2
	v_cvt_f32_ubyte0_e32 v150, v2
	v_rcp_f32_e32 v149, v1
	v_pk_add_f32 v[150:151], v[150:151], 0.5 op_sel_hi:[1,0]
	v_cvt_f32_ubyte0_e32 v1, v145
	v_pk_mul_f32 v[146:147], v[150:151], v[146:147]
	v_add_f32_e32 v1, 0.5, v1
	v_pk_mul_f32 v[8:9], v[8:9], v[146:147]
	v_rcp_f32_e32 v146, v1
	v_cvt_f32_ubyte1_e32 v1, v145
	v_add_f32_e32 v1, 0.5, v1
	v_rcp_f32_e32 v147, v1
	v_cvt_f32_ubyte2_e32 v1, v145
	v_add_f32_e32 v1, 0.5, v1
	v_rcp_f32_e32 v144, v1
	v_cvt_f32_ubyte3_e32 v1, v145
	v_cvt_f32_ubyte3_e32 v153, v2
	v_cvt_f32_ubyte2_e32 v152, v2
	v_add_f32_e32 v1, 0.5, v1
	v_pk_add_f32 v[152:153], v[152:153], 0.5 op_sel_hi:[1,0]
	v_rcp_f32_e32 v145, v1
	v_pk_mul_f32 v[148:149], v[152:153], v[148:149]
	v_cvt_f32_ubyte3_e32 v151, v3
	v_pk_mul_f32 v[10:11], v[10:11], v[148:149]
	v_cvt_f32_ubyte1_e32 v149, v3
	v_cvt_f32_ubyte0_e32 v148, v3
	v_cvt_f32_ubyte2_e32 v150, v3
	v_pk_add_f32 v[2:3], v[150:151], 0.5 op_sel_hi:[1,0]
	v_pk_add_f32 v[148:149], v[148:149], 0.5 op_sel_hi:[1,0]
	v_pk_mul_f32 v[2:3], v[2:3], v[144:145]
	v_pk_mul_f32 v[146:147], v[148:149], v[146:147]
	v_pk_mul_f32 v[6:7], v[6:7], v[2:3]
	v_pk_mul_f32 v[4:5], v[4:5], v[146:147]
	s_branch .LBB0_44
